# scan loop: DPP wait-state slots of the y reduction filled with the next step's first pk_mul (and its counted wait); two address copies removed
# speedup vs baseline: 1.0132x; 1.0132x over previous
.LBB0_764:
	v_pk_mul_f32 v[104:105], v[38:39], v[86:87]
	v_pk_mul_f32 v[38:39], v[38:39], v[94:95]
	v_pk_mul_f32 v[106:107], v[34:35], v[90:91]
	v_pk_mul_f32 v[34:35], v[34:35], v[98:99]
	v_pk_fma_f32 v[104:105], v[40:41], v[88:89], v[104:105]
	v_pk_fma_f32 v[38:39], v[40:41], v[96:97], v[38:39]
	v_pk_fma_f32 v[40:41], v[36:37], v[92:93], v[106:107]
	v_pk_fma_f32 v[34:35], v[36:37], v[100:101], v[34:35]
	v_pk_add_f32 v[36:37], v[40:41], v[104:105]
	v_pk_add_f32 v[34:35], v[34:35], v[38:39]
	v_add_f32_e32 v36, v36, v37
	v_add_f32_e32 v34, v34, v35
	ds_read_b128 v[54:57], v114
	ds_read_b128 v[50:53], v114 offset:16
	ds_read_b128 v[78:81], v114 offset:256
	ds_read_b128 v[74:77], v114 offset:272
	ds_read_b128 v[70:73], v114 offset:512
	ds_read_b128 v[66:69], v114 offset:528
	ds_read_b128 v[62:65], v114 offset:768
	ds_read_b128 v[58:61], v114 offset:784
	ds_read_b128 v[46:49], v114 offset:1024
	ds_read_b128 v[42:45], v114 offset:1040
	v_add_f32_dpp v35, v36, v36 quad_perm:[1,0,3,2] row_mask:0xf bank_mask:0xf bound_ctrl:1
	v_add_f32_dpp v34, v34, v34 quad_perm:[1,0,3,2] row_mask:0xf bank_mask:0xf bound_ctrl:1
	v_add_f32_dpp v35, v35, v35 quad_perm:[2,3,0,1] row_mask:0xf bank_mask:0xf bound_ctrl:1
	v_add_f32_dpp v36, v34, v34 quad_perm:[2,3,0,1] row_mask:0xf bank_mask:0xf bound_ctrl:1
	ds_read2_b32 v[102:103], v85 offset1:32
	v_add_f32_dpp v34, v35, v35 row_half_mirror row_mask:0xf bank_mask:0xf bound_ctrl:1
	v_add_f32_dpp v36, v36, v36 row_half_mirror row_mask:0xf bank_mask:0xf bound_ctrl:1
	v_pk_mul_f32 v[38:39], v[22:23], v[34:35] op_sel_hi:[1,0]
	v_pk_mul_f32 v[22:23], v[22:23], v[36:37] op_sel_hi:[1,0]
	v_pk_mul_f32 v[40:41], v[24:25], v[34:35] op_sel_hi:[1,0]
	v_pk_mul_f32 v[24:25], v[24:25], v[36:37] op_sel_hi:[1,0]
	v_pk_mul_f32 v[104:105], v[18:19], v[34:35] op_sel_hi:[1,0]
	v_pk_mul_f32 v[18:19], v[18:19], v[36:37] op_sel_hi:[1,0]
	v_pk_mul_f32 v[34:35], v[20:21], v[34:35] op_sel_hi:[1,0]
	v_pk_mul_f32 v[20:21], v[20:21], v[36:37] op_sel_hi:[1,0]
	v_pk_fma_f32 v[36:37], v[30:31], v[82:83], v[38:39] op_sel_hi:[1,0,1]
	v_pk_fma_f32 v[22:23], v[30:31], v[84:85], v[22:23] op_sel_hi:[1,0,1]
	v_pk_fma_f32 v[30:31], v[32:33], v[82:83], v[40:41] op_sel_hi:[1,0,1]
	v_pk_fma_f32 v[24:25], v[32:33], v[84:85], v[24:25] op_sel_hi:[1,0,1]
	v_pk_fma_f32 v[32:33], v[26:27], v[82:83], v[104:105] op_sel_hi:[1,0,1]
	v_pk_fma_f32 v[18:19], v[26:27], v[84:85], v[18:19] op_sel_hi:[1,0,1]
	v_pk_fma_f32 v[26:27], v[28:29], v[82:83], v[34:35] op_sel_hi:[1,0,1]
	v_pk_fma_f32 v[20:21], v[28:29], v[84:85], v[20:21] op_sel_hi:[1,0,1]
	v_pk_fma_f32 v[86:87], v[6:7], v[86:87], v[36:37]
	v_pk_fma_f32 v[94:95], v[6:7], v[94:95], v[22:23]
	v_pk_fma_f32 v[90:91], v[2:3], v[90:91], v[32:33]
	v_pk_fma_f32 v[98:99], v[2:3], v[98:99], v[18:19]
	v_pk_fma_f32 v[88:89], v[8:9], v[88:89], v[30:31]
	v_pk_fma_f32 v[96:97], v[8:9], v[96:97], v[24:25]
	v_pk_fma_f32 v[92:93], v[4:5], v[92:93], v[26:27]
	v_pk_fma_f32 v[100:101], v[4:5], v[100:101], v[20:21]
	s_waitcnt lgkmcnt(12)
	v_pk_mul_f32 v[2:3], v[14:15], v[86:87]
	v_pk_mul_f32 v[4:5], v[14:15], v[94:95]
	s_waitcnt lgkmcnt(11)
	v_pk_mul_f32 v[6:7], v[10:11], v[90:91]
	v_pk_mul_f32 v[8:9], v[10:11], v[98:99]
	v_pk_fma_f32 v[2:3], v[16:17], v[88:89], v[2:3]
	v_pk_fma_f32 v[4:5], v[16:17], v[96:97], v[4:5]
	v_pk_fma_f32 v[6:7], v[12:13], v[92:93], v[6:7]
	v_pk_fma_f32 v[8:9], v[12:13], v[100:101], v[8:9]
	v_pk_add_f32 v[2:3], v[2:3], v[6:7]
	v_pk_add_f32 v[4:5], v[4:5], v[8:9]
	v_add_f32_e32 v2, v2, v3
	v_add_f32_e32 v3, v4, v5
	v_add_u32_e32 v115, 0x1c000, v1
	v_add_f32_dpp v2, v2, v2 quad_perm:[1,0,3,2] row_mask:0xf bank_mask:0xf bound_ctrl:1
	v_add_f32_dpp v3, v3, v3 quad_perm:[1,0,3,2] row_mask:0xf bank_mask:0xf bound_ctrl:1
	s_waitcnt lgkmcnt(8)
	v_add_f32_dpp v2, v2, v2 quad_perm:[2,3,0,1] row_mask:0xf bank_mask:0xf bound_ctrl:1
	v_add_f32_dpp v3, v3, v3 quad_perm:[2,3,0,1] row_mask:0xf bank_mask:0xf bound_ctrl:1
	v_pk_mul_f32 v[104:105], v[78:79], v[86:87]
	v_add_f32_dpp v2, v2, v2 row_half_mirror row_mask:0xf bank_mask:0xf bound_ctrl:1
	v_add_f32_dpp v3, v3, v3 row_half_mirror row_mask:0xf bank_mask:0xf bound_ctrl:1
	s_and_saveexec_b64 s[8:9], s[42:43]
	ds_write2_b32 v115, v2, v3 offset0:0 offset1:32
.LBB0_766:
	s_or_b64 exec, exec, s[8:9]
	v_pk_mul_f32 v[78:79], v[78:79], v[94:95]
	s_waitcnt lgkmcnt(7)
	v_pk_mul_f32 v[106:107], v[74:75], v[90:91]
	v_pk_mul_f32 v[74:75], v[74:75], v[98:99]
	v_pk_fma_f32 v[104:105], v[80:81], v[88:89], v[104:105]
	v_pk_fma_f32 v[78:79], v[80:81], v[96:97], v[78:79]
	v_pk_fma_f32 v[80:81], v[76:77], v[92:93], v[106:107]
	v_pk_fma_f32 v[74:75], v[76:77], v[100:101], v[74:75]
	v_pk_add_f32 v[76:77], v[104:105], v[80:81]
	v_pk_add_f32 v[74:75], v[78:79], v[74:75]
	v_add_f32_e32 v76, v76, v77
	v_add_f32_e32 v74, v74, v75
	s_waitcnt lgkmcnt(0)
	v_mov_b32_e32 v78, v103
	v_add_f32_dpp v75, v76, v76 quad_perm:[1,0,3,2] row_mask:0xf bank_mask:0xf bound_ctrl:1
	v_add_f32_dpp v74, v74, v74 quad_perm:[1,0,3,2] row_mask:0xf bank_mask:0xf bound_ctrl:1
	ds_read_b128 v[6:9], v114 offset:1536
	ds_read_b128 v[2:5], v114 offset:1552
	ds_read_b128 v[38:41], v114 offset:1792
	ds_read_b128 v[34:37], v114 offset:1808
	ds_read_b128 v[22:25], v114 offset:2048
	ds_read_b128 v[18:21], v114 offset:2064
	v_add_f32_dpp v75, v75, v75 quad_perm:[2,3,0,1] row_mask:0xf bank_mask:0xf bound_ctrl:1
	v_add_f32_dpp v76, v74, v74 quad_perm:[2,3,0,1] row_mask:0xf bank_mask:0xf bound_ctrl:1
	v_add_u32_e32 v10, 0x400, v85
	v_add_f32_dpp v74, v75, v75 row_half_mirror row_mask:0xf bank_mask:0xf bound_ctrl:1
	v_add_f32_dpp v76, v76, v76 row_half_mirror row_mask:0xf bank_mask:0xf bound_ctrl:1
	v_pk_mul_f32 v[80:81], v[70:71], v[74:75] op_sel_hi:[1,0]
	v_pk_mul_f32 v[70:71], v[70:71], v[76:77] op_sel_hi:[1,0]
	v_pk_mul_f32 v[104:105], v[72:73], v[74:75] op_sel_hi:[1,0]
	v_pk_mul_f32 v[72:73], v[72:73], v[76:77] op_sel_hi:[1,0]
	v_pk_mul_f32 v[106:107], v[66:67], v[74:75] op_sel_hi:[1,0]
	v_pk_mul_f32 v[66:67], v[66:67], v[76:77] op_sel_hi:[1,0]
	v_pk_mul_f32 v[74:75], v[68:69], v[74:75] op_sel_hi:[1,0]
	v_pk_mul_f32 v[68:69], v[68:69], v[76:77] op_sel_hi:[1,0]
	v_pk_fma_f32 v[76:77], v[62:63], v[102:103], v[80:81] op_sel_hi:[1,0,1]
	v_pk_fma_f32 v[62:63], v[62:63], v[78:79], v[70:71] op_sel_hi:[1,0,1]
	v_pk_fma_f32 v[70:71], v[64:65], v[102:103], v[104:105] op_sel_hi:[1,0,1]
	v_pk_fma_f32 v[64:65], v[64:65], v[78:79], v[72:73] op_sel_hi:[1,0,1]
	v_pk_fma_f32 v[72:73], v[58:59], v[102:103], v[106:107] op_sel_hi:[1,0,1]
	v_pk_fma_f32 v[58:59], v[58:59], v[78:79], v[66:67] op_sel_hi:[1,0,1]
	v_pk_fma_f32 v[66:67], v[60:61], v[102:103], v[74:75] op_sel_hi:[1,0,1]
	v_pk_fma_f32 v[60:61], v[60:61], v[78:79], v[68:69] op_sel_hi:[1,0,1]
	v_pk_fma_f32 v[102:103], v[54:55], v[86:87], v[76:77]
	v_pk_fma_f32 v[94:95], v[54:55], v[94:95], v[62:63]
	v_pk_fma_f32 v[106:107], v[50:51], v[90:91], v[72:73]
	v_pk_fma_f32 v[108:109], v[50:51], v[98:99], v[58:59]
	v_pk_fma_f32 v[104:105], v[56:57], v[88:89], v[70:71]
	v_pk_fma_f32 v[96:97], v[56:57], v[96:97], v[64:65]
	v_pk_fma_f32 v[110:111], v[52:53], v[92:93], v[66:67]
	v_pk_fma_f32 v[112:113], v[52:53], v[100:101], v[60:61]
	v_pk_mul_f32 v[50:51], v[46:47], v[102:103]
	v_pk_mul_f32 v[46:47], v[46:47], v[94:95]
	v_pk_mul_f32 v[52:53], v[42:43], v[106:107]
	v_pk_mul_f32 v[42:43], v[42:43], v[108:109]
	v_pk_fma_f32 v[50:51], v[48:49], v[104:105], v[50:51]
	v_pk_fma_f32 v[46:47], v[48:49], v[96:97], v[46:47]
	v_pk_fma_f32 v[48:49], v[44:45], v[110:111], v[52:53]
	v_pk_fma_f32 v[42:43], v[44:45], v[112:113], v[42:43]
	v_pk_add_f32 v[44:45], v[50:51], v[48:49]
	v_pk_add_f32 v[42:43], v[46:47], v[42:43]
	v_add_f32_e32 v44, v44, v45
	v_add_f32_e32 v42, v42, v43
	ds_read2_b32 v[82:83], v10 offset0:128 offset1:160
	ds_read_b128 v[30:33], v114 offset:2304
	ds_read_b128 v[26:29], v114 offset:2320
	ds_read_b128 v[14:17], v114 offset:2560
	ds_read_b128 v[10:13], v114 offset:2576
	v_add_f32_dpp v43, v44, v44 quad_perm:[1,0,3,2] row_mask:0xf bank_mask:0xf bound_ctrl:1
	v_add_f32_dpp v44, v42, v42 quad_perm:[1,0,3,2] row_mask:0xf bank_mask:0xf bound_ctrl:1
	s_waitcnt lgkmcnt(4)
	v_mov_b32_e32 v84, v83
	v_add_f32_dpp v42, v43, v43 quad_perm:[2,3,0,1] row_mask:0xf bank_mask:0xf bound_ctrl:1
	v_add_f32_dpp v43, v44, v44 quad_perm:[2,3,0,1] row_mask:0xf bank_mask:0xf bound_ctrl:1
	v_pk_mul_f32 v[88:89], v[38:39], v[102:103]
	v_add_f32_dpp v42, v42, v42 row_half_mirror row_mask:0xf bank_mask:0xf bound_ctrl:1
	v_add_f32_dpp v43, v43, v43 row_half_mirror row_mask:0xf bank_mask:0xf bound_ctrl:1
	s_and_saveexec_b64 s[8:9], s[42:43]
	ds_write2_b32 v115, v42, v43 offset0:64 offset1:96
; __device__ __forceinline__ void rwkv_unit(LAS unsigned char* lds, const LAS Params* PL, int b, int h, const int tid) {
;     ...
;             f32x4 Pd0, Pd1, Pn0, Pn1, Pe0, Pe1, Pk0, Pk1, Pr0, Pr1, Qd0, Qd1, Qn0, Qn1, Qe0, Qe1, Qk0, Qk1, Qr0, Qr1; float Pva, Pvb, Qva, Qvb;
;             RW_LV(P, 0);
; #pragma unroll 2
;             for (int tl = 0; tl < TC; tl += 2) {
;                 RW_LV(Q, tl + 1);
;                 RW_ROW2(P, tl * 64);
;                 if (tl + 2 < TC) RW_LV(P, tl + 2);
.LBB0_768:
	s_or_b64 exec, exec, s[8:9]
	v_pk_mul_f32 v[90:91], v[38:39], v[94:95]
	v_pk_mul_f32 v[92:93], v[34:35], v[106:107]
	v_pk_mul_f32 v[98:99], v[34:35], v[108:109]
	v_pk_fma_f32 v[88:89], v[40:41], v[104:105], v[88:89]
	v_pk_fma_f32 v[90:91], v[40:41], v[96:97], v[90:91]
	v_pk_fma_f32 v[92:93], v[36:37], v[110:111], v[92:93]
	v_pk_fma_f32 v[98:99], v[36:37], v[112:113], v[98:99]
	v_add_u32_e32 v83, 0xc00, v85
	v_pk_add_f32 v[88:89], v[92:93], v[88:89]
	v_pk_add_f32 v[90:91], v[98:99], v[90:91]
	ds_read_b128 v[54:57], v114 offset:3072
	ds_read_b128 v[50:53], v114 offset:3088
	ds_read_b128 v[78:81], v114 offset:3328
	ds_read_b128 v[74:77], v114 offset:3344
	ds_read_b128 v[70:73], v114 offset:3584
	ds_read_b128 v[66:69], v114 offset:3600
	ds_read_b128 v[62:65], v114 offset:3840
	ds_read_b128 v[58:61], v114 offset:3856
	ds_read_b128 v[46:49], v114 offset:4096
	ds_read_b128 v[42:45], v114 offset:4112
	ds_read2_b32 v[86:87], v83 offset1:32
	v_add_f32_e32 v83, v88, v89
	v_add_f32_e32 v88, v90, v91
	s_nop 0
	v_add_f32_dpp v83, v83, v83 quad_perm:[1,0,3,2] row_mask:0xf bank_mask:0xf bound_ctrl:1
	v_add_f32_dpp v88, v88, v88 quad_perm:[1,0,3,2] row_mask:0xf bank_mask:0xf bound_ctrl:1
	s_nop 0
	v_add_f32_dpp v83, v83, v83 quad_perm:[2,3,0,1] row_mask:0xf bank_mask:0xf bound_ctrl:1
	v_add_f32_dpp v89, v88, v88 quad_perm:[2,3,0,1] row_mask:0xf bank_mask:0xf bound_ctrl:1
	s_nop 0
	v_add_f32_dpp v88, v83, v83 row_half_mirror row_mask:0xf bank_mask:0xf bound_ctrl:1
	v_add_f32_dpp v90, v89, v89 row_half_mirror row_mask:0xf bank_mask:0xf bound_ctrl:1
	v_pk_mul_f32 v[92:93], v[22:23], v[88:89] op_sel_hi:[1,0]
	v_pk_mul_f32 v[98:99], v[22:23], v[90:91] op_sel_hi:[1,0]
	v_pk_mul_f32 v[100:101], v[24:25], v[88:89] op_sel_hi:[1,0]
	v_pk_mul_f32 v[120:121], v[18:19], v[88:89] op_sel_hi:[1,0]
	v_pk_mul_f32 v[122:123], v[18:19], v[90:91] op_sel_hi:[1,0]
	v_pk_mul_f32 v[118:119], v[24:25], v[90:91] op_sel_hi:[1,0]
	v_pk_mul_f32 v[88:89], v[20:21], v[88:89] op_sel_hi:[1,0]
	v_pk_mul_f32 v[90:91], v[20:21], v[90:91] op_sel_hi:[1,0]
	s_waitcnt lgkmcnt(14)
	v_pk_fma_f32 v[92:93], v[30:31], v[82:83], v[92:93] op_sel_hi:[1,0,1]
	v_pk_fma_f32 v[98:99], v[30:31], v[84:85], v[98:99] op_sel_hi:[1,0,1]
	v_pk_fma_f32 v[100:101], v[32:33], v[82:83], v[100:101] op_sel_hi:[1,0,1]
	s_waitcnt lgkmcnt(13)
	v_pk_fma_f32 v[120:121], v[26:27], v[82:83], v[120:121] op_sel_hi:[1,0,1]
	v_pk_fma_f32 v[122:123], v[26:27], v[84:85], v[122:123] op_sel_hi:[1,0,1]
	v_pk_fma_f32 v[118:119], v[32:33], v[84:85], v[118:119] op_sel_hi:[1,0,1]
	v_pk_fma_f32 v[124:125], v[28:29], v[82:83], v[88:89] op_sel_hi:[1,0,1]
	v_pk_fma_f32 v[126:127], v[28:29], v[84:85], v[90:91] op_sel_hi:[1,0,1]
	v_pk_fma_f32 v[88:89], v[6:7], v[102:103], v[92:93]
	v_pk_fma_f32 v[90:91], v[6:7], v[94:95], v[98:99]
	v_pk_fma_f32 v[92:93], v[8:9], v[104:105], v[100:101]
	v_pk_fma_f32 v[98:99], v[2:3], v[106:107], v[120:121]
	v_pk_fma_f32 v[100:101], v[2:3], v[108:109], v[122:123]
	v_pk_fma_f32 v[96:97], v[8:9], v[96:97], v[118:119]
	v_pk_fma_f32 v[102:103], v[4:5], v[110:111], v[124:125]
	v_pk_fma_f32 v[104:105], v[4:5], v[112:113], v[126:127]
	s_waitcnt lgkmcnt(12)
	v_pk_mul_f32 v[94:95], v[14:15], v[88:89]
	v_pk_mul_f32 v[106:107], v[14:15], v[90:91]
	s_waitcnt lgkmcnt(11)
	v_pk_mul_f32 v[108:109], v[10:11], v[98:99]
	v_pk_mul_f32 v[110:111], v[10:11], v[100:101]
	v_pk_fma_f32 v[94:95], v[16:17], v[92:93], v[94:95]
	v_pk_fma_f32 v[106:107], v[16:17], v[96:97], v[106:107]
	v_pk_fma_f32 v[108:109], v[12:13], v[102:103], v[108:109]
	v_pk_fma_f32 v[110:111], v[12:13], v[104:105], v[110:111]
	v_pk_add_f32 v[94:95], v[94:95], v[108:109]
	v_pk_add_f32 v[106:107], v[106:107], v[110:111]
	v_add_f32_e32 v83, v94, v95
	v_add_f32_e32 v94, v106, v107
	s_nop 0
	v_add_f32_dpp v83, v83, v83 quad_perm:[1,0,3,2] row_mask:0xf bank_mask:0xf bound_ctrl:1
	v_add_f32_dpp v94, v94, v94 quad_perm:[1,0,3,2] row_mask:0xf bank_mask:0xf bound_ctrl:1
	s_nop 0
	v_add_f32_dpp v83, v83, v83 quad_perm:[2,3,0,1] row_mask:0xf bank_mask:0xf bound_ctrl:1
	v_add_f32_dpp v94, v94, v94 quad_perm:[2,3,0,1] row_mask:0xf bank_mask:0xf bound_ctrl:1
	s_nop 0
	v_add_f32_dpp v83, v83, v83 row_half_mirror row_mask:0xf bank_mask:0xf bound_ctrl:1
	v_add_f32_dpp v94, v94, v94 row_half_mirror row_mask:0xf bank_mask:0xf bound_ctrl:1
	s_and_saveexec_b64 s[8:9], s[42:43]
	ds_write2_b32 v115, v83, v94 offset0:128 offset1:160
.LBB0_770:
	s_or_b64 exec, exec, s[8:9]
	s_cmp_gt_u32 s18, 29
	s_cselect_b64 s[8:9], -1, 0
	s_and_b64 vcc, exec, s[8:9]
	s_cbranch_vccnz .LBB0_772
	ds_read_b128 v[6:9], v114 offset:4608
	ds_read_b128 v[2:5], v114 offset:4624
	ds_read_b128 v[38:41], v114 offset:4864
	ds_read_b128 v[34:37], v114 offset:4880
	ds_read_b128 v[22:25], v114 offset:5120
	ds_read_b128 v[18:21], v114 offset:5136
	ds_read_b128 v[30:33], v114 offset:5376
	ds_read_b128 v[26:29], v114 offset:5392
	v_add_u32_e32 v10, 0x1000, v85
	ds_read2_b32 v[82:83], v10 offset0:128 offset1:160
	ds_read_b128 v[14:17], v114 offset:5632
	ds_read_b128 v[10:13], v114 offset:5648
	s_waitcnt lgkmcnt(2)
	v_mov_b32_e32 v84, v83
